# GEMM K-loops with every s_setprio flip deleted and no static raise (all waves at priority 0)
# baseline (speedup 1.0000x reference)
; template <class Epi, class Sched, bool ALIGN_EPI = false, bool SP2 = false>
; __device__ __forceinline__ void gemm_phase(PG8_LAS unsigned char* lds, const Gemm g, const Sched& S, const Epi& E, const int tid_in) {
;     ...
; #pragma unroll
;         for (int a = 0; a < 2; ++a)
; #pragma unroll
;             for (int b = 0; b < 2; ++b)
; #pragma unroll
;                 for (int m = 0; m < 4; ++m)
; #pragma unroll
;                     for (int n = 0; n < 2; ++n) acc[a][b][m][n] = (f32x4){0.f, 0.f, 0.f, 0.f};
;         cur = nxt; cA = nA; cB = nB; ++ui;
.LBB0_119:
	s_add_u32 s56, s8, 0x100
	v_mov_b32_e32 v0, 0
	s_addc_u32 s57, s9, 0
	s_mov_b32 s58, -2
	v_mov_b32_e32 v1, v0
	v_mov_b32_e32 v2, v0
	v_mov_b32_e32 v3, v0
	v_mov_b32_e32 v4, v0
	v_mov_b32_e32 v5, v0
	v_mov_b32_e32 v6, v0
	v_mov_b32_e32 v7, v0
	v_mov_b32_e32 v8, v0
	v_mov_b32_e32 v9, v0
	v_mov_b32_e32 v10, v0
	v_mov_b32_e32 v11, v0
	v_mov_b32_e32 v16, v0
	v_mov_b32_e32 v17, v0
	v_mov_b32_e32 v18, v0
	v_mov_b32_e32 v19, v0
	v_mov_b32_e32 v24, v0
	v_mov_b32_e32 v25, v0
	v_mov_b32_e32 v26, v0
	v_mov_b32_e32 v27, v0
	v_mov_b32_e32 v32, v0
	v_mov_b32_e32 v33, v0
	v_mov_b32_e32 v34, v0
	v_mov_b32_e32 v35, v0
	v_mov_b32_e32 v40, v0
	v_mov_b32_e32 v41, v0
	v_mov_b32_e32 v42, v0
	v_mov_b32_e32 v43, v0
	v_mov_b32_e32 v48, v0
	v_mov_b32_e32 v49, v0
	v_mov_b32_e32 v50, v0
	v_mov_b32_e32 v51, v0
	v_mov_b32_e32 v12, v0
	v_mov_b32_e32 v13, v0
	v_mov_b32_e32 v14, v0
	v_mov_b32_e32 v15, v0
	v_mov_b32_e32 v20, v0
	v_mov_b32_e32 v21, v0
	v_mov_b32_e32 v22, v0
	v_mov_b32_e32 v23, v0
	v_mov_b32_e32 v28, v0
	v_mov_b32_e32 v29, v0
	v_mov_b32_e32 v30, v0
	v_mov_b32_e32 v31, v0
	v_mov_b32_e32 v36, v0
	v_mov_b32_e32 v37, v0
	v_mov_b32_e32 v38, v0
	v_mov_b32_e32 v39, v0
	v_mov_b32_e32 v44, v0
	v_mov_b32_e32 v45, v0
	v_mov_b32_e32 v46, v0
	v_mov_b32_e32 v47, v0
	v_mov_b32_e32 v52, v0
	v_mov_b32_e32 v53, v0
	v_mov_b32_e32 v54, v0
	v_mov_b32_e32 v55, v0
	v_mov_b32_e32 v56, v0
	v_mov_b32_e32 v57, v0
	v_mov_b32_e32 v58, v0
	v_mov_b32_e32 v59, v0
	v_mov_b32_e32 v60, v0
	v_mov_b32_e32 v61, v0
	v_mov_b32_e32 v62, v0
	v_mov_b32_e32 v63, v0
	v_mov_b32_e32 v64, v0
	v_mov_b32_e32 v65, v0
	v_mov_b32_e32 v66, v0
	v_mov_b32_e32 v67, v0
	v_mov_b32_e32 v68, v0
	v_mov_b32_e32 v69, v0
	v_mov_b32_e32 v70, v0
	v_mov_b32_e32 v71, v0
	v_mov_b32_e32 v80, v0
	v_mov_b32_e32 v81, v0
	v_mov_b32_e32 v82, v0
	v_mov_b32_e32 v83, v0
	v_mov_b32_e32 v84, v0
	v_mov_b32_e32 v85, v0
	v_mov_b32_e32 v86, v0
	v_mov_b32_e32 v87, v0
	v_mov_b32_e32 v98, v0
	v_mov_b32_e32 v99, v0
	v_mov_b32_e32 v100, v0
	v_mov_b32_e32 v101, v0
	v_mov_b32_e32 v102, v0
	v_mov_b32_e32 v103, v0
	v_mov_b32_e32 v104, v0
	v_mov_b32_e32 v105, v0
	v_mov_b32_e32 v130, v0
	v_mov_b32_e32 v131, v0
	v_mov_b32_e32 v132, v0
	v_mov_b32_e32 v133, v0
	v_mov_b32_e32 v134, v0
	v_mov_b32_e32 v135, v0
	v_mov_b32_e32 v136, v0
	v_mov_b32_e32 v137, v0
	v_mov_b32_e32 v72, v0
	v_mov_b32_e32 v73, v0
	v_mov_b32_e32 v74, v0
	v_mov_b32_e32 v75, v0
	v_mov_b32_e32 v76, v0
	v_mov_b32_e32 v77, v0
	v_mov_b32_e32 v78, v0
	v_mov_b32_e32 v79, v0
	v_mov_b32_e32 v88, v0
	v_mov_b32_e32 v89, v0
	v_mov_b32_e32 v90, v0
	v_mov_b32_e32 v91, v0
	v_mov_b32_e32 v92, v0
	v_mov_b32_e32 v93, v0
	v_mov_b32_e32 v94, v0
	v_mov_b32_e32 v95, v0
	v_mov_b32_e32 v106, v0
	v_mov_b32_e32 v107, v0
	v_mov_b32_e32 v108, v0
	v_mov_b32_e32 v109, v0
	v_mov_b32_e32 v110, v0
	v_mov_b32_e32 v111, v0
	v_mov_b32_e32 v112, v0
	v_mov_b32_e32 v113, v0
	v_mov_b32_e32 v138, v0
	v_mov_b32_e32 v139, v0
	v_mov_b32_e32 v140, v0
	v_mov_b32_e32 v141, v0
	v_mov_b32_e32 v142, v0
	v_mov_b32_e32 v143, v0
	v_mov_b32_e32 v144, v0
	v_mov_b32_e32 v145, v0
	v_readfirstlane_b32 s70, v241
	s_nop 3
	s_lshr_b32 s70, s70, 6
	s_cmp_ge_u32 s70, 4
	s_cbranch_scc0 .Lprio_done_120

; template <class Epi, class Sched, bool ALIGN_EPI = false, bool SP2 = false>
; __device__ __forceinline__ void gemm_phase(PG8_LAS unsigned char* lds, const Gemm g, const Sched& S, const Epi& E, const int tid_in) {
;     ...
;         const bool has_next = S.next(ui + 1, nxt);
;         const char* nA = has_next ? (const char*)g.A + (size_t)nxt.pm * tstep : cA; const char* nB = has_next ? (const char*)g.Bt + (size_t)nxt.pn * tstep : cB;
;     ...
; #pragma unroll
;         for (int a = 0; a < 2; ++a)
; #pragma unroll
;             for (int b = 0; b < 2; ++b)
; #pragma unroll
;                 for (int m = 0; m < 4; ++m)
; #pragma unroll
;                     for (int n = 0; n < 2; ++n) acc[a][b][m][n] = (f32x4){0.f, 0.f, 0.f, 0.f};
;         cur = nxt; cA = nA; cB = nB; ++ui;
.LBB0_137:
	s_ashr_i32 s43, s42, 31
	s_lshl_b64 s[12:13], s[42:43], 20
	v_readlane_b32 s44, v255, 4
	v_readlane_b32 s45, v255, 5
	s_add_u32 s44, s44, s12
	s_addc_u32 s45, s45, s13
	s_and_b64 s[12:13], s[38:39], exec
	s_cselect_b32 s12, s45, s11
	s_cselect_b32 s13, s44, s10
	s_ashr_i32 s41, s40, 31
	s_lshl_b64 s[48:49], s[40:41], 20
	s_add_u32 s48, s14, s48
	s_addc_u32 s49, s15, s49
	s_and_b64 s[50:51], s[38:39], exec
	s_cselect_b32 s41, s49, s9
	s_cselect_b32 s43, s48, s8
	s_add_u32 s50, s10, 0x80080
	s_addc_u32 s51, s11, 0
	s_add_u32 s56, s8, 0x100
	v_mov_b32_e32 v0, 0
	s_addc_u32 s57, s9, 0
	s_mov_b32 s58, -2
	v_mov_b32_e32 v1, v0
	v_mov_b32_e32 v2, v0
	v_mov_b32_e32 v3, v0
	v_mov_b32_e32 v8, v0
	v_mov_b32_e32 v9, v0
	v_mov_b32_e32 v10, v0
	v_mov_b32_e32 v11, v0
	v_mov_b32_e32 v16, v0
	v_mov_b32_e32 v17, v0
	v_mov_b32_e32 v18, v0
	v_mov_b32_e32 v19, v0
	v_mov_b32_e32 v24, v0
	v_mov_b32_e32 v25, v0
	v_mov_b32_e32 v26, v0
	v_mov_b32_e32 v27, v0
	v_mov_b32_e32 v32, v0
	v_mov_b32_e32 v33, v0
	v_mov_b32_e32 v34, v0
	v_mov_b32_e32 v35, v0
	v_mov_b32_e32 v40, v0
	v_mov_b32_e32 v41, v0
	v_mov_b32_e32 v42, v0
	v_mov_b32_e32 v43, v0
	v_mov_b32_e32 v48, v0
	v_mov_b32_e32 v49, v0
	v_mov_b32_e32 v50, v0
	v_mov_b32_e32 v51, v0
	v_mov_b32_e32 v56, v0
	v_mov_b32_e32 v57, v0
	v_mov_b32_e32 v58, v0
	v_mov_b32_e32 v59, v0
	v_mov_b32_e32 v4, v0
	v_mov_b32_e32 v5, v0
	v_mov_b32_e32 v6, v0
	v_mov_b32_e32 v7, v0
	v_mov_b32_e32 v12, v0
	v_mov_b32_e32 v13, v0
	v_mov_b32_e32 v14, v0
	v_mov_b32_e32 v15, v0
	v_mov_b32_e32 v20, v0
	v_mov_b32_e32 v21, v0
	v_mov_b32_e32 v22, v0
	v_mov_b32_e32 v23, v0
	v_mov_b32_e32 v28, v0
	v_mov_b32_e32 v29, v0
	v_mov_b32_e32 v30, v0
	v_mov_b32_e32 v31, v0
	v_mov_b32_e32 v36, v0
	v_mov_b32_e32 v37, v0
	v_mov_b32_e32 v38, v0
	v_mov_b32_e32 v39, v0
	v_mov_b32_e32 v44, v0
	v_mov_b32_e32 v45, v0
	v_mov_b32_e32 v46, v0
	v_mov_b32_e32 v47, v0
	v_mov_b32_e32 v52, v0
	v_mov_b32_e32 v53, v0
	v_mov_b32_e32 v54, v0
	v_mov_b32_e32 v55, v0
	v_mov_b32_e32 v60, v0
	v_mov_b32_e32 v61, v0
	v_mov_b32_e32 v62, v0
	v_mov_b32_e32 v63, v0
	v_mov_b32_e32 v64, v0
	v_mov_b32_e32 v65, v0
	v_mov_b32_e32 v66, v0
	v_mov_b32_e32 v67, v0
	v_mov_b32_e32 v72, v0
	v_mov_b32_e32 v73, v0
	v_mov_b32_e32 v74, v0
	v_mov_b32_e32 v75, v0
	v_mov_b32_e32 v80, v0
	v_mov_b32_e32 v81, v0
	v_mov_b32_e32 v82, v0
	v_mov_b32_e32 v83, v0
	v_mov_b32_e32 v88, v0
	v_mov_b32_e32 v89, v0
	v_mov_b32_e32 v90, v0
	v_mov_b32_e32 v91, v0
	v_mov_b32_e32 v98, v0
	v_mov_b32_e32 v99, v0
	v_mov_b32_e32 v100, v0
	v_mov_b32_e32 v101, v0
	v_mov_b32_e32 v106, v0
	v_mov_b32_e32 v107, v0
	v_mov_b32_e32 v108, v0
	v_mov_b32_e32 v109, v0
	v_mov_b32_e32 v114, v0
	v_mov_b32_e32 v115, v0
	v_mov_b32_e32 v116, v0
	v_mov_b32_e32 v117, v0
	v_mov_b32_e32 v122, v0
	v_mov_b32_e32 v123, v0
	v_mov_b32_e32 v124, v0
	v_mov_b32_e32 v125, v0
	v_mov_b32_e32 v68, v0
	v_mov_b32_e32 v69, v0
	v_mov_b32_e32 v70, v0
	v_mov_b32_e32 v71, v0
	v_mov_b32_e32 v76, v0
	v_mov_b32_e32 v77, v0
	v_mov_b32_e32 v78, v0
	v_mov_b32_e32 v79, v0
	v_mov_b32_e32 v84, v0
	v_mov_b32_e32 v85, v0
	v_mov_b32_e32 v86, v0
	v_mov_b32_e32 v87, v0
	v_mov_b32_e32 v92, v0
	v_mov_b32_e32 v93, v0
	v_mov_b32_e32 v94, v0
	v_mov_b32_e32 v95, v0
	v_mov_b32_e32 v102, v0
	v_mov_b32_e32 v103, v0
	v_mov_b32_e32 v104, v0
	v_mov_b32_e32 v105, v0
	v_mov_b32_e32 v110, v0
	v_mov_b32_e32 v111, v0
	v_mov_b32_e32 v112, v0
	v_mov_b32_e32 v113, v0
	v_mov_b32_e32 v118, v0
	v_mov_b32_e32 v119, v0
	v_mov_b32_e32 v120, v0
	v_mov_b32_e32 v121, v0
	v_mov_b32_e32 v126, v0
	v_mov_b32_e32 v127, v0
	v_mov_b32_e32 v128, v0
	v_mov_b32_e32 v129, v0
	v_readfirstlane_b32 s70, v241
	s_nop 3
	s_lshr_b32 s70, s70, 6
	s_cmp_ge_u32 s70, 4
	s_cbranch_scc0 .Lprio_done_138

; template <class Epi, class Sched, bool ALIGN_EPI = false, bool SP2 = false>
; __device__ __forceinline__ void gemm_phase(PG8_LAS unsigned char* lds, const Gemm g, const Sched& S, const Epi& E, const int tid_in) {
;     ...
;         const bool has_next = S.next(ui + 1, nxt);
;         const char* nA = has_next ? (const char*)g.A + (size_t)nxt.pm * tstep : cA; const char* nB = has_next ? (const char*)g.Bt + (size_t)nxt.pn * tstep : cB;
;     ...
; #pragma unroll
;         for (int a = 0; a < 2; ++a)
; #pragma unroll
;             for (int b = 0; b < 2; ++b)
; #pragma unroll
;                 for (int m = 0; m < 4; ++m)
; #pragma unroll
;                     for (int n = 0; n < 2; ++n) acc[a][b][m][n] = (f32x4){0.f, 0.f, 0.f, 0.f};
;         cur = nxt; cA = nA; cB = nB; ++ui;
.LBB0_179:
	s_ashr_i32 s43, s42, 31
	s_lshl_b64 s[12:13], s[42:43], 20
	v_readlane_b32 s44, v255, 4
	v_readlane_b32 s45, v255, 5
	s_add_u32 s44, s44, s12
	s_addc_u32 s45, s45, s13
	s_and_b64 s[12:13], s[38:39], exec
	s_cselect_b32 s12, s45, s11
	s_cselect_b32 s13, s44, s10
	s_ashr_i32 s41, s40, 31
	s_lshl_b64 s[48:49], s[40:41], 20
	s_add_u32 s48, s14, s48
	s_addc_u32 s49, s15, s49
	s_and_b64 s[50:51], s[38:39], exec
	s_cselect_b32 s41, s49, s9
	s_cselect_b32 s43, s48, s8
	s_add_u32 s50, s10, 0x80080
	s_addc_u32 s51, s11, 0
	s_add_u32 s58, s8, 0x100
	v_mov_b32_e32 v0, 0
	s_addc_u32 s59, s9, 0
	s_mov_b32 s60, -2
	v_mov_b32_e32 v1, v0
	v_mov_b32_e32 v2, v0
	v_mov_b32_e32 v3, v0
	v_mov_b32_e32 v4, v0
	v_mov_b32_e32 v5, v0
	v_mov_b32_e32 v6, v0
	v_mov_b32_e32 v7, v0
	v_mov_b32_e32 v8, v0
	v_mov_b32_e32 v9, v0
	v_mov_b32_e32 v10, v0
	v_mov_b32_e32 v11, v0
	v_mov_b32_e32 v16, v0
	v_mov_b32_e32 v17, v0
	v_mov_b32_e32 v18, v0
	v_mov_b32_e32 v19, v0
	v_mov_b32_e32 v24, v0
	v_mov_b32_e32 v25, v0
	v_mov_b32_e32 v26, v0
	v_mov_b32_e32 v27, v0
	v_mov_b32_e32 v32, v0
	v_mov_b32_e32 v33, v0
	v_mov_b32_e32 v34, v0
	v_mov_b32_e32 v35, v0
	v_mov_b32_e32 v40, v0
	v_mov_b32_e32 v41, v0
	v_mov_b32_e32 v42, v0
	v_mov_b32_e32 v43, v0
	v_mov_b32_e32 v48, v0
	v_mov_b32_e32 v49, v0
	v_mov_b32_e32 v50, v0
	v_mov_b32_e32 v51, v0
	v_mov_b32_e32 v12, v0
	v_mov_b32_e32 v13, v0
	v_mov_b32_e32 v14, v0
	v_mov_b32_e32 v15, v0
	v_mov_b32_e32 v20, v0
	v_mov_b32_e32 v21, v0
	v_mov_b32_e32 v22, v0
	v_mov_b32_e32 v23, v0
	v_mov_b32_e32 v28, v0
	v_mov_b32_e32 v29, v0
	v_mov_b32_e32 v30, v0
	v_mov_b32_e32 v31, v0
	v_mov_b32_e32 v36, v0
	v_mov_b32_e32 v37, v0
	v_mov_b32_e32 v38, v0
	v_mov_b32_e32 v39, v0
	v_mov_b32_e32 v44, v0
	v_mov_b32_e32 v45, v0
	v_mov_b32_e32 v46, v0
	v_mov_b32_e32 v47, v0
	v_mov_b32_e32 v52, v0
	v_mov_b32_e32 v53, v0
	v_mov_b32_e32 v54, v0
	v_mov_b32_e32 v55, v0
	v_mov_b32_e32 v56, v0
	v_mov_b32_e32 v57, v0
	v_mov_b32_e32 v58, v0
	v_mov_b32_e32 v59, v0
	v_mov_b32_e32 v60, v0
	v_mov_b32_e32 v61, v0
	v_mov_b32_e32 v62, v0
	v_mov_b32_e32 v63, v0
	v_mov_b32_e32 v64, v0
	v_mov_b32_e32 v65, v0
	v_mov_b32_e32 v66, v0
	v_mov_b32_e32 v67, v0
	v_mov_b32_e32 v68, v0
	v_mov_b32_e32 v69, v0
	v_mov_b32_e32 v70, v0
	v_mov_b32_e32 v71, v0
	v_mov_b32_e32 v80, v0
	v_mov_b32_e32 v81, v0
	v_mov_b32_e32 v82, v0
	v_mov_b32_e32 v83, v0
	v_mov_b32_e32 v84, v0
	v_mov_b32_e32 v85, v0
	v_mov_b32_e32 v86, v0
	v_mov_b32_e32 v87, v0
	v_mov_b32_e32 v98, v0
	v_mov_b32_e32 v99, v0
	v_mov_b32_e32 v100, v0
	v_mov_b32_e32 v101, v0
	v_mov_b32_e32 v102, v0
	v_mov_b32_e32 v103, v0
	v_mov_b32_e32 v104, v0
	v_mov_b32_e32 v105, v0
	v_mov_b32_e32 v130, v0
	v_mov_b32_e32 v131, v0
	v_mov_b32_e32 v132, v0
	v_mov_b32_e32 v133, v0
	v_mov_b32_e32 v134, v0
	v_mov_b32_e32 v135, v0
	v_mov_b32_e32 v136, v0
	v_mov_b32_e32 v137, v0
	v_mov_b32_e32 v72, v0
	v_mov_b32_e32 v73, v0
	v_mov_b32_e32 v74, v0
	v_mov_b32_e32 v75, v0
	v_mov_b32_e32 v76, v0
	v_mov_b32_e32 v77, v0
	v_mov_b32_e32 v78, v0
	v_mov_b32_e32 v79, v0
	v_mov_b32_e32 v88, v0
	v_mov_b32_e32 v89, v0
	v_mov_b32_e32 v90, v0
	v_mov_b32_e32 v91, v0
	v_mov_b32_e32 v92, v0
	v_mov_b32_e32 v93, v0
	v_mov_b32_e32 v94, v0
	v_mov_b32_e32 v95, v0
	v_mov_b32_e32 v106, v0
	v_mov_b32_e32 v107, v0
	v_mov_b32_e32 v108, v0
	v_mov_b32_e32 v109, v0
	v_mov_b32_e32 v110, v0
	v_mov_b32_e32 v111, v0
	v_mov_b32_e32 v112, v0
	v_mov_b32_e32 v113, v0
	v_mov_b32_e32 v138, v0
	v_mov_b32_e32 v139, v0
	v_mov_b32_e32 v140, v0
	v_mov_b32_e32 v141, v0
	v_mov_b32_e32 v142, v0
	v_mov_b32_e32 v143, v0
	v_mov_b32_e32 v144, v0
	v_mov_b32_e32 v145, v0
	v_readfirstlane_b32 s70, v241
	s_nop 3
	s_lshr_b32 s70, s70, 6
	s_cmp_ge_u32 s70, 4
	s_cbranch_scc0 .Lprio_done_180

; template <class Epi, class Sched, bool ALIGN_EPI = false, bool SP2 = false>
; __device__ __forceinline__ void gemm_phase(PG8_LAS unsigned char* lds, const Gemm g, const Sched& S, const Epi& E, const int tid_in) {
;     ...
;         const bool has_next = S.next(ui + 1, nxt);
;         const char* nA = has_next ? (const char*)g.A + (size_t)nxt.pm * tstep : cA; const char* nB = has_next ? (const char*)g.Bt + (size_t)nxt.pn * tstep : cB;
;     ...
; #pragma unroll
;         for (int a = 0; a < 2; ++a)
; #pragma unroll
;             for (int b = 0; b < 2; ++b)
; #pragma unroll
;                 for (int m = 0; m < 4; ++m)
; #pragma unroll
;                     for (int n = 0; n < 2; ++n) acc[a][b][m][n] = (f32x4){0.f, 0.f, 0.f, 0.f};
;         cur = nxt; cA = nA; cB = nB; ++ui;
.LBB0_592:
	s_ashr_i32 s57, s56, 31
	s_lshl_b64 s[12:13], s[56:57], 20
	v_readlane_b32 s36, v255, 4
	v_readlane_b32 s37, v255, 5
	s_add_u32 s36, s36, s12
	s_addc_u32 s37, s37, s13
	s_and_b64 s[12:13], s[38:39], exec
	s_cselect_b32 s12, s37, s11
	s_cselect_b32 s13, s36, s10
	s_ashr_i32 s55, s54, 31
	s_lshl_b64 s[42:43], s[54:55], 20
	s_add_u32 s58, s14, s42
	s_addc_u32 s59, s15, s43
	s_and_b64 s[42:43], s[38:39], exec
	s_cselect_b32 s41, s59, s9
	s_cselect_b32 s44, s58, s8
	s_add_u32 s42, s10, 0x80080
	s_addc_u32 s43, s11, 0
	s_add_u32 s45, s8, 0x100
	v_mov_b32_e32 v0, 0
	s_addc_u32 s55, s9, 0
	s_mov_b32 s57, -2
	v_mov_b32_e32 v1, v0
	v_mov_b32_e32 v2, v0
	v_mov_b32_e32 v3, v0
	v_mov_b32_e32 v4, v0
	v_mov_b32_e32 v5, v0
	v_mov_b32_e32 v6, v0
	v_mov_b32_e32 v7, v0
	v_mov_b32_e32 v16, v0
	v_mov_b32_e32 v17, v0
	v_mov_b32_e32 v18, v0
	v_mov_b32_e32 v19, v0
	v_mov_b32_e32 v20, v0
	v_mov_b32_e32 v21, v0
	v_mov_b32_e32 v22, v0
	v_mov_b32_e32 v23, v0
	v_mov_b32_e32 v32, v0
	v_mov_b32_e32 v33, v0
	v_mov_b32_e32 v34, v0
	v_mov_b32_e32 v35, v0
	v_mov_b32_e32 v36, v0
	v_mov_b32_e32 v37, v0
	v_mov_b32_e32 v38, v0
	v_mov_b32_e32 v39, v0
	v_mov_b32_e32 v48, v0
	v_mov_b32_e32 v49, v0
	v_mov_b32_e32 v50, v0
	v_mov_b32_e32 v51, v0
	v_mov_b32_e32 v52, v0
	v_mov_b32_e32 v53, v0
	v_mov_b32_e32 v54, v0
	v_mov_b32_e32 v55, v0
	v_mov_b32_e32 v8, v0
	v_mov_b32_e32 v9, v0
	v_mov_b32_e32 v10, v0
	v_mov_b32_e32 v11, v0
	v_mov_b32_e32 v12, v0
	v_mov_b32_e32 v13, v0
	v_mov_b32_e32 v14, v0
	v_mov_b32_e32 v15, v0
	v_mov_b32_e32 v24, v0
	v_mov_b32_e32 v25, v0
	v_mov_b32_e32 v26, v0
	v_mov_b32_e32 v27, v0
	v_mov_b32_e32 v28, v0
	v_mov_b32_e32 v29, v0
	v_mov_b32_e32 v30, v0
	v_mov_b32_e32 v31, v0
	v_mov_b32_e32 v40, v0
	v_mov_b32_e32 v41, v0
	v_mov_b32_e32 v42, v0
	v_mov_b32_e32 v43, v0
	v_mov_b32_e32 v44, v0
	v_mov_b32_e32 v45, v0
	v_mov_b32_e32 v46, v0
	v_mov_b32_e32 v47, v0
	v_mov_b32_e32 v56, v0
	v_mov_b32_e32 v57, v0
	v_mov_b32_e32 v58, v0
	v_mov_b32_e32 v59, v0
	v_mov_b32_e32 v60, v0
	v_mov_b32_e32 v61, v0
	v_mov_b32_e32 v62, v0
	v_mov_b32_e32 v63, v0
	v_mov_b32_e32 v72, v0
	v_mov_b32_e32 v73, v0
	v_mov_b32_e32 v74, v0
	v_mov_b32_e32 v75, v0
	v_mov_b32_e32 v76, v0
	v_mov_b32_e32 v77, v0
	v_mov_b32_e32 v78, v0
	v_mov_b32_e32 v79, v0
	v_mov_b32_e32 v98, v0
	v_mov_b32_e32 v99, v0
	v_mov_b32_e32 v100, v0
	v_mov_b32_e32 v101, v0
	v_mov_b32_e32 v102, v0
	v_mov_b32_e32 v103, v0
	v_mov_b32_e32 v104, v0
	v_mov_b32_e32 v105, v0
	v_mov_b32_e32 v122, v0
	v_mov_b32_e32 v123, v0
	v_mov_b32_e32 v124, v0
	v_mov_b32_e32 v125, v0
	v_mov_b32_e32 v126, v0
	v_mov_b32_e32 v127, v0
	v_mov_b32_e32 v128, v0
	v_mov_b32_e32 v129, v0
	v_mov_b32_e32 v146, v0
	v_mov_b32_e32 v147, v0
	v_mov_b32_e32 v148, v0
	v_mov_b32_e32 v149, v0
	v_mov_b32_e32 v150, v0
	v_mov_b32_e32 v151, v0
	v_mov_b32_e32 v152, v0
	v_mov_b32_e32 v153, v0
	v_mov_b32_e32 v80, v0
	v_mov_b32_e32 v81, v0
	v_mov_b32_e32 v82, v0
	v_mov_b32_e32 v83, v0
	v_mov_b32_e32 v84, v0
	v_mov_b32_e32 v85, v0
	v_mov_b32_e32 v86, v0
	v_mov_b32_e32 v87, v0
	v_mov_b32_e32 v114, v0
	v_mov_b32_e32 v115, v0
	v_mov_b32_e32 v116, v0
	v_mov_b32_e32 v117, v0
	v_mov_b32_e32 v118, v0
	v_mov_b32_e32 v119, v0
	v_mov_b32_e32 v120, v0
	v_mov_b32_e32 v121, v0
	v_mov_b32_e32 v138, v0
	v_mov_b32_e32 v139, v0
	v_mov_b32_e32 v140, v0
	v_mov_b32_e32 v141, v0
	v_mov_b32_e32 v142, v0
	v_mov_b32_e32 v143, v0
	v_mov_b32_e32 v144, v0
	v_mov_b32_e32 v145, v0
	v_mov_b32_e32 v154, v0
	v_mov_b32_e32 v155, v0
	v_mov_b32_e32 v156, v0
	v_mov_b32_e32 v157, v0
	v_mov_b32_e32 v158, v0
	v_mov_b32_e32 v159, v0
	v_mov_b32_e32 v160, v0
	v_mov_b32_e32 v161, v0
	v_readfirstlane_b32 s70, v241
	s_nop 3
	s_lshr_b32 s70, s70, 6
	s_cmp_ge_u32 s70, 4
	s_cbranch_scc0 .Lprio_done_593
